# DSA attention gathers: selected-row list zero-filled past nsel so per-row selects dropped; row address = one v_lshl_or on a scalar base
# speedup vs baseline: 1.0066x; 1.0066x over previous
.LBB0_2485:
	v_cmp_ge_i32_e32 vcc, s54, v186
	s_nop 1
	v_cndmask_b32_e32 v0, 0, v186, vcc
	ds_write_b32 v163, v0
	v_add_u32_e32 v2, 64, v186
	v_cmp_ge_i32_e32 vcc, s54, v2
	s_nop 1
	v_cndmask_b32_e32 v0, 0, v2, vcc
	ds_write_b32 v163, v0 offset:256
	v_add_u32_e32 v2, 128, v186
	v_cmp_ge_i32_e32 vcc, s54, v2
	s_nop 1
	v_cndmask_b32_e32 v0, 0, v2, vcc
	ds_write_b32 v163, v0 offset:512
	v_add_u32_e32 v2, 192, v186
	v_cmp_ge_i32_e32 vcc, s54, v2
	s_nop 1
	v_cndmask_b32_e32 v0, 0, v2, vcc
	ds_write_b32 v163, v0 offset:768
	s_mov_b64 s[6:7], exec

.LBB0_2489:
	s_waitcnt lgkmcnt(0)
	s_andn2_b64 vcc, exec, s[28:29]
	s_cbranch_vccnz .LBB0_1626
	s_add_i32 s6, s54, s16
	s_ashr_i32 s7, s6, 31
	s_lshl_b64 s[10:11], s[6:7], 12
	v_lshl_add_u64 v[2:3], v[170:171], 0, s[10:11]
	global_load_dwordx4 v[4:7], v[2:3], off
	global_load_dwordx4 v[8:11], v[2:3], off offset:64
	global_load_dwordx4 v[12:15], v[2:3], off offset:128
	global_load_dwordx4 v[16:19], v[2:3], off offset:192
	s_lshl_b32 s16, s16, 8
	v_readfirstlane_b32 s96, v174
	v_readfirstlane_b32 s97, v175
	v_and_b32_e32 v152, 15, v192
	v_lshlrev_b32_e32 v152, 4, v152
	s_nop 1
	s_add_u32 s96, s96, s16
	s_addc_u32 s97, s97, 0
	ds_read_b32 v20, v213
	ds_read_b32 v24, v213 offset:16
	ds_read_b32 v28, v213 offset:32
	ds_read_b32 v64, v213 offset:48
	ds_read_b32 v72, v213 offset:64
	ds_read_b32 v80, v213 offset:80
	ds_read_b32 v88, v213 offset:96
	ds_read_b32 v96, v213 offset:112
	ds_read_b32 v68, v213 offset:128
	ds_read_b32 v76, v213 offset:144
	ds_read_b32 v84, v213 offset:160
	ds_read_b32 v92, v213 offset:176
	ds_read_b32 v100, v213 offset:192
	ds_read_b32 v104, v213 offset:208
	ds_read_b32 v108, v213 offset:224
	ds_read_b32 v112, v213 offset:240
	s_waitcnt lgkmcnt(0)
	v_lshl_or_b32 v20, v20, 8, v152
	global_load_dwordx4 v[20:23], v20, s[96:97]
	v_lshl_or_b32 v24, v24, 8, v152
	global_load_dwordx4 v[24:27], v24, s[96:97]
	v_lshl_or_b32 v28, v28, 8, v152
	global_load_dwordx4 v[28:31], v28, s[96:97]
	v_lshl_or_b32 v64, v64, 8, v152
	global_load_dwordx4 v[64:67], v64, s[96:97]
	v_lshl_or_b32 v72, v72, 8, v152
	global_load_dwordx4 v[72:75], v72, s[96:97]
	v_lshl_or_b32 v80, v80, 8, v152
	global_load_dwordx4 v[80:83], v80, s[96:97]
	v_lshl_or_b32 v88, v88, 8, v152
	global_load_dwordx4 v[88:91], v88, s[96:97]
	v_lshl_or_b32 v96, v96, 8, v152
	global_load_dwordx4 v[96:99], v96, s[96:97]
	v_lshl_or_b32 v68, v68, 8, v152
	global_load_dwordx4 v[68:71], v68, s[96:97]
	v_lshl_or_b32 v76, v76, 8, v152
	global_load_dwordx4 v[76:79], v76, s[96:97]
	v_lshl_or_b32 v84, v84, 8, v152
	global_load_dwordx4 v[84:87], v84, s[96:97]
	v_lshl_or_b32 v92, v92, 8, v152
	global_load_dwordx4 v[92:95], v92, s[96:97]
	v_lshl_or_b32 v100, v100, 8, v152
	global_load_dwordx4 v[100:103], v100, s[96:97]
	v_lshl_or_b32 v104, v104, 8, v152
	global_load_dwordx4 v[104:107], v104, s[96:97]
	v_lshl_or_b32 v108, v108, 8, v152
	global_load_dwordx4 v[108:111], v108, s[96:97]
	v_lshl_or_b32 v112, v112, 8, v152
	global_load_dwordx4 v[112:115], v112, s[96:97]
	s_add_i32 s6, s40, 31
	s_ashr_i32 s16, s6, 5
	s_cmp_gt_i32 s16, 0
	s_cbranch_scc0 .LBB0_1624
	v_mov_b32_e32 v2, v1
	v_mov_b32_e32 v3, v1
	v_mov_b32_e32 v0, v1
	v_mov_b32_e32 v154, 0
	v_mov_b64_e32 v[34:35], v[2:3]
	v_mov_b64_e32 v[38:39], v[2:3]
	v_mov_b64_e32 v[42:43], v[2:3]
	v_mov_b64_e32 v[46:47], v[2:3]
	v_mov_b64_e32 v[50:51], v[2:3]
	v_mov_b64_e32 v[54:55], v[2:3]
	v_mov_b64_e32 v[58:59], v[2:3]
	v_mov_b64_e32 v[62:63], v[2:3]
	s_mov_b32 s41, 0
	v_mov_b32_e32 v230, 0xff800000
	s_mov_b32 s55, 3
	s_mov_b32 s57, s42
	v_mov_b64_e32 v[32:33], v[0:1]
	v_mov_b64_e32 v[36:37], v[0:1]
	v_mov_b64_e32 v[40:41], v[0:1]
	v_mov_b64_e32 v[44:45], v[0:1]
	v_mov_b64_e32 v[48:49], v[0:1]
	v_mov_b64_e32 v[52:53], v[0:1]
	v_mov_b64_e32 v[56:57], v[0:1]
	v_mov_b64_e32 v[60:61], v[0:1]
	v_mov_b32_e32 v231, 0xff800000
	v_mov_b32_e32 v232, 0xff800000
	v_mov_b32_e32 v233, 0xff800000
	v_mov_b32_e32 v155, v154
	v_mov_b32_e32 v156, v154
	v_mov_b32_e32 v157, v154
	s_branch .LBB0_2526

.LBB0_2526:
	s_add_i32 s58, s55, -1
	s_cmp_ge_i32 s58, s16
	s_waitcnt vmcnt(0)
	ds_write_b128 v218, v[20:23]
	ds_write_b128 v218, v[24:27] offset:1088
	ds_write_b128 v218, v[28:31] offset:2176
	ds_write_b128 v218, v[64:67] offset:3264
	ds_write_b128 v218, v[72:75] offset:4352
	ds_write_b128 v218, v[80:83] offset:5440
	ds_write_b128 v218, v[88:91] offset:6528
	ds_write_b128 v218, v[96:99] offset:7616
	s_cbranch_scc1 .LBB0_2544
	v_add_u32_e32 v98, s57, v212
	v_add_u32_e32 v98, 0x20100, v98
	ds_read_b32 v20, v98
	ds_read_b32 v24, v98 offset:16
	ds_read_b32 v28, v98 offset:32
	ds_read_b32 v64, v98 offset:48
	ds_read_b32 v72, v98 offset:64
	ds_read_b32 v80, v98 offset:80
	ds_read_b32 v88, v98 offset:96
	ds_read_b32 v96, v98 offset:112
	s_waitcnt lgkmcnt(0)
	v_lshl_or_b32 v20, v20, 8, v152
	global_load_dwordx4 v[20:23], v20, s[96:97]
	v_lshl_or_b32 v24, v24, 8, v152
	global_load_dwordx4 v[24:27], v24, s[96:97]
	v_lshl_or_b32 v28, v28, 8, v152
	global_load_dwordx4 v[28:31], v28, s[96:97]
	v_lshl_or_b32 v64, v64, 8, v152
	global_load_dwordx4 v[64:67], v64, s[96:97]
	v_lshl_or_b32 v72, v72, 8, v152
	global_load_dwordx4 v[72:75], v72, s[96:97]
	v_lshl_or_b32 v80, v80, 8, v152
	global_load_dwordx4 v[80:83], v80, s[96:97]
	v_lshl_or_b32 v88, v88, 8, v152
	global_load_dwordx4 v[88:91], v88, s[96:97]
	v_lshl_or_b32 v96, v96, 8, v152
	global_load_dwordx4 v[96:99], v96, s[96:97]

.LBB0_2554:
	s_waitcnt lgkmcnt(0)
	v_mfma_f32_16x16x32_bf16 v[60:63], v[116:119], v[148:151], v[60:63]
	v_fma_f32 v2, v156, v160, v2
	v_fma_f32 v3, v157, v161, v3
	s_add_i32 s6, s55, -2
	v_pk_add_f32 v[156:157], v[158:159], v[2:3]
	v_mfma_f32_16x16x32_bf16 v[56:59], v[116:119], v[144:147], v[56:59]
	v_fma_f32 v2, v154, v184, v180
	v_fma_f32 v3, v155, v185, v181
	s_cmp_ge_i32 s6, s16
	v_pk_add_f32 v[154:155], v[182:183], v[2:3]
	v_mfma_f32_16x16x32_bf16 v[52:55], v[116:119], v[140:143], v[52:55]
	v_mfma_f32_16x16x32_bf16 v[48:51], v[116:119], v[136:139], v[48:51]
	v_mfma_f32_16x16x32_bf16 v[44:47], v[116:119], v[132:135], v[44:47]
	v_mfma_f32_16x16x32_bf16 v[40:43], v[116:119], v[128:131], v[40:43]
	v_mfma_f32_16x16x32_bf16 v[36:39], v[116:119], v[124:127], v[36:39]
	v_mfma_f32_16x16x32_bf16 v[32:35], v[116:119], v[120:123], v[32:35]
	s_cbranch_scc1 .LBB0_2524
	s_cmp_ge_i32 s55, s16
	ds_write_b128 v218, v[68:71]
	ds_write_b128 v218, v[76:79] offset:1088
	ds_write_b128 v218, v[84:87] offset:2176
	ds_write_b128 v218, v[92:95] offset:3264
	ds_write_b128 v218, v[100:103] offset:4352
	ds_write_b128 v218, v[104:107] offset:5440
	ds_write_b128 v218, v[108:111] offset:6528
	ds_write_b128 v218, v[112:115] offset:7616
	s_cbranch_scc1 .LBB0_2573
	v_add_u32_e32 v114, s57, v212
	v_add_u32_e32 v114, 0x20180, v114
	ds_read_b32 v68, v114
	ds_read_b32 v76, v114 offset:16
	ds_read_b32 v84, v114 offset:32
	ds_read_b32 v92, v114 offset:48
	ds_read_b32 v100, v114 offset:64
	ds_read_b32 v104, v114 offset:80
	ds_read_b32 v108, v114 offset:96
	ds_read_b32 v112, v114 offset:112
	s_waitcnt lgkmcnt(0)
	v_lshl_or_b32 v68, v68, 8, v152
	global_load_dwordx4 v[68:71], v68, s[96:97]
	v_lshl_or_b32 v76, v76, 8, v152
	global_load_dwordx4 v[76:79], v76, s[96:97]
	v_lshl_or_b32 v84, v84, 8, v152
	global_load_dwordx4 v[84:87], v84, s[96:97]
	v_lshl_or_b32 v92, v92, 8, v152
	global_load_dwordx4 v[92:95], v92, s[96:97]
	v_lshl_or_b32 v100, v100, 8, v152
	global_load_dwordx4 v[100:103], v100, s[96:97]
	v_lshl_or_b32 v104, v104, 8, v152
	global_load_dwordx4 v[104:107], v104, s[96:97]
	v_lshl_or_b32 v108, v108, 8, v152
	global_load_dwordx4 v[108:111], v108, s[96:97]
	v_lshl_or_b32 v112, v112, 8, v152
	global_load_dwordx4 v[112:115], v112, s[96:97]
